# layer-prep weight conversion loops unrolled by two with both iterations loads in flight (two register sets)
# speedup vs baseline: 1.0006x; 1.0006x over previous
; __device__ __forceinline__ unsigned cvt_pk_bf16(float lo, float hi) { const f32x2_ v = {lo, hi}; return __builtin_bit_cast(unsigned, __builtin_convertvector(v, bf16x2_)); }
; __device__ __forceinline__ int opaque_tid() { int t = threadIdx.x; asm volatile("" : "+v"(t)); return t; }
; template <class F>
; __device__ __forceinline__ void wt_rows64(bf16_t* dst, int K, F srcval, int ldd, int kbeg, int kend) {
;     if (ldd == 0) ldd = K;
;     if (kend > K) kend = K;
;     const int tid_ = opaque_tid(); const int nl = tid_ & 63, kq = tid_ >> 6;
;     for (int k0 = kbeg + kq * 8; k0 < kend; k0 += 64) {
;         float v[8];
; #pragma unroll
;         for (int j = 0; j < 8; ++j) v[j] = srcval(nl, k0 + j);
;         u32x4 w; w.x = cvt_pk_bf16(v[0], v[1]); w.y = cvt_pk_bf16(v[2], v[3]); w.z = cvt_pk_bf16(v[4], v[5]); w.w = cvt_pk_bf16(v[6], v[7]);
;         *(u32x4*)(dst + (size_t)nl * ldd + k0) = w;
;     }
.LBB0_805:
	v_add_u32_e32 v32, 6, v1
	v_add_u32_e32 v34, 7, v1
	v_lshl_add_u64 v[20:21], v[18:19], 0, v[2:3]
	v_lshl_add_u64 v[22:23], v[14:15], 0, v[2:3]
	v_lshl_add_u64 v[24:25], v[12:13], 0, v[2:3]
	v_lshl_add_u64 v[26:27], v[10:11], 0, v[2:3]
	v_ashrrev_i32_e32 v33, 31, v32
	v_ashrrev_i32_e32 v35, 31, v34
	v_lshl_add_u64 v[28:29], v[8:9], 0, v[2:3]
	v_lshl_add_u64 v[30:31], v[6:7], 0, v[2:3]
	global_load_dword v36, v[20:21], off
	global_load_dword v37, v[22:23], off
	s_nop 0
	global_load_dword v24, v[24:25], off
	s_nop 0
	global_load_dword v25, v[26:27], off
	s_nop 0
	global_load_dword v26, v[28:29], off
	global_load_dword v27, v[30:31], off
	v_lshlrev_b64 v[20:21], 12, v[32:33]
	v_lshlrev_b64 v[22:23], 12, v[34:35]
	v_lshl_add_u64 v[20:21], v[4:5], 0, v[20:21]
	v_lshl_add_u64 v[22:23], v[4:5], 0, v[22:23]
	global_load_dword v28, v[20:21], off
	s_nop 0
	global_load_dword v23, v[22:23], off
	v_add_u32_e32 v1, 64, v1
	v_cmp_le_i32_e32 vcc, s4, v1
	v_lshl_add_u64 v[6:7], v[6:7], 0, s[96:97]
	v_lshl_add_u64 v[8:9], v[8:9], 0, s[96:97]
	v_lshl_add_u64 v[10:11], v[10:11], 0, s[96:97]
	v_lshl_add_u64 v[12:13], v[12:13], 0, s[96:97]
	v_lshl_add_u64 v[14:15], v[14:15], 0, s[96:97]
	v_lshl_add_u64 v[18:19], v[18:19], 0, s[96:97]
	s_or_b64 s[0:1], vcc, s[0:1]
	s_andn2_b64 vcc, exec, s[0:1]
	s_cbranch_vccz .Lwt_tail0
	v_add_u32_e32 v72, 6, v1
	v_add_u32_e32 v74, 7, v1
	v_lshl_add_u64 v[60:61], v[18:19], 0, v[2:3]
	v_lshl_add_u64 v[62:63], v[14:15], 0, v[2:3]
	v_lshl_add_u64 v[64:65], v[12:13], 0, v[2:3]
	v_lshl_add_u64 v[66:67], v[10:11], 0, v[2:3]
	v_ashrrev_i32_e32 v73, 31, v72
	v_ashrrev_i32_e32 v75, 31, v74
	v_lshl_add_u64 v[68:69], v[8:9], 0, v[2:3]
	v_lshl_add_u64 v[70:71], v[6:7], 0, v[2:3]
	global_load_dword v76, v[60:61], off
	global_load_dword v77, v[62:63], off
	s_nop 0
	global_load_dword v64, v[64:65], off
	s_nop 0
	global_load_dword v65, v[66:67], off
	s_nop 0
	global_load_dword v66, v[68:69], off
	global_load_dword v67, v[70:71], off
	v_lshlrev_b64 v[60:61], 12, v[72:73]
	v_lshlrev_b64 v[62:63], 12, v[74:75]
	v_lshl_add_u64 v[60:61], v[4:5], 0, v[60:61]
	v_lshl_add_u64 v[62:63], v[4:5], 0, v[62:63]
	global_load_dword v68, v[60:61], off
	s_nop 0
	global_load_dword v63, v[62:63], off
	v_add_u32_e32 v1, 64, v1
	v_cmp_le_i32_e32 vcc, s4, v1
	v_lshl_add_u64 v[6:7], v[6:7], 0, s[96:97]
	v_lshl_add_u64 v[8:9], v[8:9], 0, s[96:97]
	v_lshl_add_u64 v[10:11], v[10:11], 0, s[96:97]
	v_lshl_add_u64 v[12:13], v[12:13], 0, s[96:97]
	v_lshl_add_u64 v[14:15], v[14:15], 0, s[96:97]
	v_lshl_add_u64 v[18:19], v[18:19], 0, s[96:97]
	s_or_b64 s[0:1], vcc, s[0:1]
	s_waitcnt vmcnt(14)
	v_cvt_pk_bf16_f32 v20, v36, v37
	s_waitcnt vmcnt(12)
	v_cvt_pk_bf16_f32 v21, v24, v25
	s_waitcnt vmcnt(10)
	v_cvt_pk_bf16_f32 v22, v26, v27
	s_waitcnt vmcnt(8)
	v_cvt_pk_bf16_f32 v23, v28, v23
	global_store_dwordx4 v[16:17], v[20:23], off
	v_lshl_add_u64 v[16:17], v[16:17], 0, s[90:91]
	s_waitcnt vmcnt(7)
	v_cvt_pk_bf16_f32 v60, v76, v77
	s_waitcnt vmcnt(5)
	v_cvt_pk_bf16_f32 v61, v64, v65
	s_waitcnt vmcnt(3)
	v_cvt_pk_bf16_f32 v62, v66, v67
	s_waitcnt vmcnt(1)
	v_cvt_pk_bf16_f32 v63, v68, v63
	global_store_dwordx4 v[16:17], v[60:63], off
	v_lshl_add_u64 v[16:17], v[16:17], 0, s[90:91]
	s_andn2_b64 exec, exec, s[0:1]
	s_cbranch_execnz .LBB0_805
	s_branch .Lwt_done0
.Lwt_tail0:
	s_waitcnt vmcnt(6)
	v_cvt_pk_bf16_f32 v20, v36, v37
	s_waitcnt vmcnt(4)
	v_cvt_pk_bf16_f32 v21, v24, v25
	s_waitcnt vmcnt(2)
	v_cvt_pk_bf16_f32 v22, v26, v27
	s_waitcnt vmcnt(0)
	v_cvt_pk_bf16_f32 v23, v28, v23
	global_store_dwordx4 v[16:17], v[20:23], off
	v_lshl_add_u64 v[16:17], v[16:17], 0, s[90:91]
	s_andn2_b64 exec, exec, s[0:1]
.Lwt_done0:
.LBB0_806:
	s_or_b64 exec, exec, s[2:3]

; __device__ __forceinline__ unsigned cvt_pk_bf16(float lo, float hi) { const f32x2_ v = {lo, hi}; return __builtin_bit_cast(unsigned, __builtin_convertvector(v, bf16x2_)); }
; __device__ __forceinline__ int opaque_tid() { int t = threadIdx.x; asm volatile("" : "+v"(t)); return t; }
; template <class F>
; __device__ __forceinline__ void wt_rows64(bf16_t* dst, int K, F srcval, int ldd, int kbeg, int kend) {
;     if (ldd == 0) ldd = K;
;     if (kend > K) kend = K;
;     const int tid_ = opaque_tid(); const int nl = tid_ & 63, kq = tid_ >> 6;
;     for (int k0 = kbeg + kq * 8; k0 < kend; k0 += 64) {
;         float v[8];
; #pragma unroll
;         for (int j = 0; j < 8; ++j) v[j] = srcval(nl, k0 + j);
;         u32x4 w; w.x = cvt_pk_bf16(v[0], v[1]); w.y = cvt_pk_bf16(v[2], v[3]); w.z = cvt_pk_bf16(v[4], v[5]); w.w = cvt_pk_bf16(v[6], v[7]);
;         *(u32x4*)(dst + (size_t)nl * ldd + k0) = w;
;     }
.LBB0_844:
	v_lshl_add_u64 v[20:21], v[18:19], 0, v[2:3]
	v_lshl_add_u64 v[22:23], v[14:15], 0, v[2:3]
	v_lshl_add_u64 v[24:25], v[12:13], 0, v[2:3]
	v_lshl_add_u64 v[26:27], v[10:11], 0, v[2:3]
	v_add_u32_e32 v32, 6, v1
	v_add_u32_e32 v33, 7, v1
	v_lshl_add_u64 v[28:29], v[8:9], 0, v[2:3]
	v_lshl_add_u64 v[30:31], v[6:7], 0, v[2:3]
	global_load_dword v34, v[20:21], off
	global_load_dword v35, v[22:23], off
	s_nop 0
	global_load_dword v24, v[24:25], off
	s_nop 0
	global_load_dword v25, v[26:27], off
	s_nop 0
	global_load_dword v26, v[28:29], off
	global_load_dword v27, v[30:31], off
	v_mad_i64_i32 v[20:21], s[6:7], v32, s93, v[4:5]
	v_mad_i64_i32 v[22:23], s[6:7], v33, s93, v[4:5]
	global_load_dword v28, v[20:21], off
	s_nop 0
	global_load_dword v23, v[22:23], off
	v_add_u32_e32 v1, 64, v1
	v_cmp_le_i32_e32 vcc, s4, v1
	v_lshl_add_u64 v[6:7], v[6:7], 0, s[50:51]
	v_lshl_add_u64 v[8:9], v[8:9], 0, s[50:51]
	v_lshl_add_u64 v[10:11], v[10:11], 0, s[50:51]
	v_lshl_add_u64 v[12:13], v[12:13], 0, s[50:51]
	v_lshl_add_u64 v[14:15], v[14:15], 0, s[50:51]
	v_lshl_add_u64 v[18:19], v[18:19], 0, s[50:51]
	s_or_b64 s[0:1], vcc, s[0:1]
	s_andn2_b64 vcc, exec, s[0:1]
	s_cbranch_vccz .Lwt_tail3
	v_lshl_add_u64 v[60:61], v[18:19], 0, v[2:3]
	v_lshl_add_u64 v[62:63], v[14:15], 0, v[2:3]
	v_lshl_add_u64 v[64:65], v[12:13], 0, v[2:3]
	v_lshl_add_u64 v[66:67], v[10:11], 0, v[2:3]
	v_add_u32_e32 v72, 6, v1
	v_add_u32_e32 v73, 7, v1
	v_lshl_add_u64 v[68:69], v[8:9], 0, v[2:3]
	v_lshl_add_u64 v[70:71], v[6:7], 0, v[2:3]
	global_load_dword v74, v[60:61], off
	global_load_dword v75, v[62:63], off
	s_nop 0
	global_load_dword v64, v[64:65], off
	s_nop 0
	global_load_dword v65, v[66:67], off
	s_nop 0
	global_load_dword v66, v[68:69], off
	global_load_dword v67, v[70:71], off
	v_mad_i64_i32 v[60:61], s[6:7], v72, s93, v[4:5]
	v_mad_i64_i32 v[62:63], s[6:7], v73, s93, v[4:5]
	global_load_dword v68, v[60:61], off
	s_nop 0
	global_load_dword v63, v[62:63], off
	v_add_u32_e32 v1, 64, v1
	v_cmp_le_i32_e32 vcc, s4, v1
	v_lshl_add_u64 v[6:7], v[6:7], 0, s[50:51]
	v_lshl_add_u64 v[8:9], v[8:9], 0, s[50:51]
	v_lshl_add_u64 v[10:11], v[10:11], 0, s[50:51]
	v_lshl_add_u64 v[12:13], v[12:13], 0, s[50:51]
	v_lshl_add_u64 v[14:15], v[14:15], 0, s[50:51]
	v_lshl_add_u64 v[18:19], v[18:19], 0, s[50:51]
	s_or_b64 s[0:1], vcc, s[0:1]
	s_waitcnt vmcnt(14)
	v_cvt_pk_bf16_f32 v20, v34, v35
	s_waitcnt vmcnt(12)
	v_cvt_pk_bf16_f32 v21, v24, v25
	s_waitcnt vmcnt(10)
	v_cvt_pk_bf16_f32 v22, v26, v27
	s_waitcnt vmcnt(8)
	v_cvt_pk_bf16_f32 v23, v28, v23
	global_store_dwordx4 v[16:17], v[20:23], off
	v_lshl_add_u64 v[16:17], v[16:17], 0, s[90:91]
	s_waitcnt vmcnt(7)
	v_cvt_pk_bf16_f32 v60, v74, v75
	s_waitcnt vmcnt(5)
	v_cvt_pk_bf16_f32 v61, v64, v65
	s_waitcnt vmcnt(3)
	v_cvt_pk_bf16_f32 v62, v66, v67
	s_waitcnt vmcnt(1)
	v_cvt_pk_bf16_f32 v63, v68, v63
	global_store_dwordx4 v[16:17], v[60:63], off
	v_lshl_add_u64 v[16:17], v[16:17], 0, s[90:91]
	s_andn2_b64 exec, exec, s[0:1]
	s_cbranch_execnz .LBB0_844
	s_branch .Lwt_done3
.Lwt_tail3:
	s_waitcnt vmcnt(6)
	v_cvt_pk_bf16_f32 v20, v34, v35
	s_waitcnt vmcnt(4)
	v_cvt_pk_bf16_f32 v21, v24, v25
	s_waitcnt vmcnt(2)
	v_cvt_pk_bf16_f32 v22, v26, v27
	s_waitcnt vmcnt(0)
	v_cvt_pk_bf16_f32 v23, v28, v23
	global_store_dwordx4 v[16:17], v[20:23], off
	v_lshl_add_u64 v[16:17], v[16:17], 0, s[90:91]
	s_andn2_b64 exec, exec, s[0:1]
.Lwt_done3:
	s_branch .LBB0_649
.LBB0_845:
	s_mov_b32 s44, 0x800000
	s_mov_b32 s45, 0x83ff
